# S5 table builder: K loop LDS reads software-pipelined by one group (counted lgkmcnt, alternate register set) and the Ty output block rewritten with 8 LDS reads in flight instead of 16 serialized ones
# speedup vs baseline: 1.0052x; 1.0052x over previous
; __device__ __forceinline__ f32x2 cmul(f32x2 a, f32x2 b) { return (f32x2){a.x * b.x - a.y * b.y, a.x * b.y + a.y * b.x}; }
; __device__ __forceinline__ void ssm_tables(const Args& a, LAS unsigned char* lds, int l, int g, const int tid) {
;     ...
;     for (int idx = tid; idx < 4096; idx += 512) { const int tau = idx >> 8, c = (idx >> 4) & 15, c2 = idx & 15; float s = 0.f;
;         for (int p = 0; p < 64; ++p) { const f32x2 w = cmul(sC[c * 64 + p], sP[tau * 64 + p]); const f32x2 b = sB[p * 16 + c2]; s += w.x * b.x - w.y * b.y; }
;         sK[idx] = s; }
.LBB0_745:
	v_and_b32_e32 v0, 0x3c0, v16
	v_lshl_add_u32 v18, v0, 3, 0
	v_lshlrev_b32_e32 v0, 1, v17
	v_and_b32_e32 v0, 0xfffffe00, v0
	v_add_u32_e32 v19, 0, v0
	ds_read_b128 v[28:31], v18 offset:8192
	ds_read_b128 v[32:35], v18 offset:8208
	ds_read_b128 v[36:39], v18 offset:8224
	ds_read_b128 v[0:3], v18 offset:8240
	ds_read_b128 v[40:43], v19 offset:16384
	ds_read_b128 v[44:47], v19 offset:16400
	ds_read_b128 v[48:51], v19 offset:16416
	ds_read_b128 v[4:7], v19 offset:16432
	ds_read2_b64 v[52:55], v9 offset1:16
	s_waitcnt lgkmcnt(4)
	v_pk_mul_f32 v[14:15], v[28:29], v[40:41]
	s_movk_i32 s16, 0xdff
	v_sub_f32_e32 v14, v14, v15
	v_mul_f32_e32 v15, v28, v41
	s_waitcnt lgkmcnt(0)
	v_mul_f32_e32 v14, v52, v14
	v_fmac_f32_e32 v15, v29, v40
	v_fma_f32 v14, -v53, v15, v14
	v_add_f32_e32 v27, 0, v14
	v_pk_mul_f32 v[14:15], v[30:31], v[42:43]
	v_cmp_lt_i32_e32 vcc, s16, v17
	v_sub_f32_e32 v14, v14, v15
	v_mul_f32_e32 v15, v30, v43
	v_fmac_f32_e32 v15, v31, v42
	ds_read2_b64 v[28:31], v9 offset0:32 offset1:48
	v_mul_f32_e32 v14, v54, v14
	v_fma_f32 v14, -v55, v15, v14
	v_add_f32_e32 v27, v27, v14
	v_pk_mul_f32 v[14:15], v[32:33], v[44:45]
	s_or_b64 s[14:15], vcc, s[14:15]
	v_sub_f32_e32 v14, v14, v15
	v_mul_f32_e32 v15, v32, v45
	s_waitcnt lgkmcnt(0)
	v_mul_f32_e32 v14, v28, v14
	v_fmac_f32_e32 v15, v33, v44
	v_fma_f32 v14, -v29, v15, v14
	v_add_f32_e32 v27, v27, v14
	v_pk_mul_f32 v[14:15], v[34:35], v[46:47]
	v_add_u32_e32 v32, 0x800, v9
	v_sub_f32_e32 v14, v14, v15
	v_mul_f32_e32 v15, v34, v47
	v_mul_f32_e32 v14, v30, v14
	v_fmac_f32_e32 v15, v35, v46
	v_fma_f32 v14, -v31, v15, v14
	ds_read2_b64 v[28:31], v9 offset0:64 offset1:80
	v_add_f32_e32 v27, v27, v14
	v_pk_mul_f32 v[14:15], v[36:37], v[48:49]
	v_add_u32_e32 v34, 0x1800, v9
	v_sub_f32_e32 v14, v14, v15
	v_mul_f32_e32 v15, v36, v49
	s_waitcnt lgkmcnt(0)
	v_mul_f32_e32 v14, v28, v14
	v_fmac_f32_e32 v15, v37, v48
	v_fma_f32 v14, -v29, v15, v14
	v_add_f32_e32 v27, v27, v14
	v_pk_mul_f32 v[14:15], v[38:39], v[50:51]
	s_nop 0
	v_sub_f32_e32 v14, v14, v15
	v_mul_f32_e32 v15, v38, v51
	v_mul_f32_e32 v14, v30, v14
	v_fmac_f32_e32 v15, v39, v50
	v_fma_f32 v14, -v31, v15, v14
	ds_read2_b64 v[28:31], v9 offset0:96 offset1:112
	v_add_f32_e32 v27, v27, v14
	v_pk_mul_f32 v[14:15], v[0:1], v[4:5]
	v_mul_f32_e32 v0, v0, v5
	v_sub_f32_e32 v14, v14, v15
	s_waitcnt lgkmcnt(0)
	v_mul_f32_e32 v14, v28, v14
	v_fmac_f32_e32 v0, v1, v4
	v_fma_f32 v0, -v29, v0, v14
	v_add_f32_e32 v4, v27, v0
	v_pk_mul_f32 v[0:1], v[2:3], v[6:7]
	s_nop 0
	v_sub_f32_e32 v0, v0, v1
	v_mul_f32_e32 v1, v2, v7
	v_mul_f32_e32 v0, v30, v0
	v_fmac_f32_e32 v1, v3, v6
	v_fma_f32 v0, -v31, v1, v0
	v_add_f32_e32 v27, v4, v0
	ds_read_b128 v[56:59], v18 offset:8256
	ds_read_b128 v[60:63], v19 offset:16448
	ds_read2_b64 v[64:67], v9 offset0:128 offset1:144
	ds_read_b128 v[0:3], v18 offset:8272
	ds_read_b128 v[4:7], v19 offset:16464
	ds_read2_b64 v[28:31], v9 offset0:160 offset1:176
	s_waitcnt lgkmcnt(4)
	v_pk_mul_f32 v[14:15], v[56:57], v[60:61]
	s_nop 0
	v_sub_f32_e32 v14, v14, v15
	v_mul_f32_e32 v56, v56, v61
	s_waitcnt lgkmcnt(3)
	v_mul_f32_e32 v14, v64, v14
	v_fmac_f32_e32 v56, v57, v60
	v_fma_f32 v56, -v65, v56, v14
	v_add_f32_e32 v60, v27, v56
	v_pk_mul_f32 v[56:57], v[58:59], v[62:63]
	s_nop 0
	v_sub_f32_e32 v56, v56, v57
	v_mul_f32_e32 v57, v58, v63
	v_mul_f32_e32 v56, v66, v56
	v_fmac_f32_e32 v57, v59, v62
	v_fma_f32 v56, -v67, v57, v56
	v_add_f32_e32 v27, v60, v56
	ds_read_b128 v[56:59], v18 offset:8288
	ds_read_b128 v[60:63], v19 offset:16480
	ds_read2_b64 v[64:67], v9 offset0:192 offset1:208
	s_waitcnt lgkmcnt(4)
	v_pk_mul_f32 v[14:15], v[0:1], v[4:5]
	s_nop 0
	v_sub_f32_e32 v14, v14, v15
	v_mul_f32_e32 v0, v0, v5
	s_waitcnt lgkmcnt(3)
	v_mul_f32_e32 v14, v28, v14
	v_fmac_f32_e32 v0, v1, v4
	v_fma_f32 v0, -v29, v0, v14
	v_add_f32_e32 v4, v27, v0
	v_pk_mul_f32 v[0:1], v[2:3], v[6:7]
	s_nop 0
	v_sub_f32_e32 v0, v0, v1
	v_mul_f32_e32 v1, v2, v7
	v_mul_f32_e32 v0, v30, v0
	v_fmac_f32_e32 v1, v3, v6
	v_fma_f32 v0, -v31, v1, v0
	v_add_f32_e32 v27, v4, v0
	ds_read_b128 v[0:3], v18 offset:8304
	ds_read_b128 v[4:7], v19 offset:16496
	ds_read2_b64 v[28:31], v9 offset0:224 offset1:240
	s_waitcnt lgkmcnt(4)
	v_pk_mul_f32 v[14:15], v[56:57], v[60:61]
	s_nop 0
	v_sub_f32_e32 v14, v14, v15
	v_mul_f32_e32 v56, v56, v61
	s_waitcnt lgkmcnt(3)
	v_mul_f32_e32 v14, v64, v14
	v_fmac_f32_e32 v56, v57, v60
	v_fma_f32 v56, -v65, v56, v14
	v_add_f32_e32 v60, v27, v56
	v_pk_mul_f32 v[56:57], v[58:59], v[62:63]
	s_nop 0
	v_sub_f32_e32 v56, v56, v57
	v_mul_f32_e32 v57, v58, v63
	v_mul_f32_e32 v56, v66, v56
	v_fmac_f32_e32 v57, v59, v62
	v_fma_f32 v56, -v67, v57, v56
	v_add_f32_e32 v27, v60, v56
	ds_read_b128 v[56:59], v18 offset:8320
	ds_read_b128 v[60:63], v19 offset:16512
	ds_read2_b64 v[64:67], v32 offset1:16
	s_waitcnt lgkmcnt(4)
	v_pk_mul_f32 v[14:15], v[0:1], v[4:5]
	s_nop 0
	v_sub_f32_e32 v14, v14, v15
	v_mul_f32_e32 v0, v0, v5
	s_waitcnt lgkmcnt(3)
	v_mul_f32_e32 v14, v28, v14
	v_fmac_f32_e32 v0, v1, v4
	v_fma_f32 v0, -v29, v0, v14
	v_add_f32_e32 v4, v27, v0
	v_pk_mul_f32 v[0:1], v[2:3], v[6:7]
	s_nop 0
	v_sub_f32_e32 v0, v0, v1
	v_mul_f32_e32 v1, v2, v7
	v_mul_f32_e32 v0, v30, v0
	v_fmac_f32_e32 v1, v3, v6
	v_fma_f32 v0, -v31, v1, v0
	v_add_f32_e32 v27, v4, v0
	ds_read_b128 v[0:3], v18 offset:8336
	ds_read_b128 v[4:7], v19 offset:16528
	ds_read2_b64 v[28:31], v32 offset0:32 offset1:48
	s_waitcnt lgkmcnt(4)
	v_pk_mul_f32 v[14:15], v[56:57], v[60:61]
	s_nop 0
	v_sub_f32_e32 v14, v14, v15
	v_mul_f32_e32 v56, v56, v61
	s_waitcnt lgkmcnt(3)
; __device__ __forceinline__ f32x2 cmul(f32x2 a, f32x2 b) { return (f32x2){a.x * b.x - a.y * b.y, a.x * b.y + a.y * b.x}; }
; __device__ __forceinline__ void ssm_tables(const Args& a, LAS unsigned char* lds, int l, int g, const int tid) {
;     ...
;     for (int idx = tid; idx < 4096; idx += 512) { const int tau = idx >> 8, c = (idx >> 4) & 15, c2 = idx & 15; float s = 0.f;
;         for (int p = 0; p < 64; ++p) { const f32x2 w = cmul(sC[c * 64 + p], sP[tau * 64 + p]); const f32x2 b = sB[p * 16 + c2]; s += w.x * b.x - w.y * b.y; }
;         sK[idx] = s; }
	v_mul_f32_e32 v14, v64, v14
	v_fmac_f32_e32 v56, v57, v60
	v_fma_f32 v56, -v65, v56, v14
	v_add_f32_e32 v60, v27, v56
	v_pk_mul_f32 v[56:57], v[58:59], v[62:63]
	s_nop 0
	v_sub_f32_e32 v56, v56, v57
	v_mul_f32_e32 v57, v58, v63
	v_mul_f32_e32 v56, v66, v56
	v_fmac_f32_e32 v57, v59, v62
	v_fma_f32 v56, -v67, v57, v56
	v_add_f32_e32 v27, v60, v56
	ds_read_b128 v[56:59], v18 offset:8352
	ds_read_b128 v[60:63], v19 offset:16544
	ds_read2_b64 v[64:67], v32 offset0:64 offset1:80
	s_waitcnt lgkmcnt(4)
	v_pk_mul_f32 v[14:15], v[0:1], v[4:5]
	s_nop 0
	v_sub_f32_e32 v14, v14, v15
	v_mul_f32_e32 v0, v0, v5
	s_waitcnt lgkmcnt(3)
	v_mul_f32_e32 v14, v28, v14
	v_fmac_f32_e32 v0, v1, v4
	v_fma_f32 v0, -v29, v0, v14
	v_add_f32_e32 v4, v27, v0
	v_pk_mul_f32 v[0:1], v[2:3], v[6:7]
	s_nop 0
	v_sub_f32_e32 v0, v0, v1
	v_mul_f32_e32 v1, v2, v7
	v_mul_f32_e32 v0, v30, v0
	v_fmac_f32_e32 v1, v3, v6
	v_fma_f32 v0, -v31, v1, v0
	v_add_f32_e32 v27, v4, v0
	ds_read_b128 v[0:3], v18 offset:8368
	ds_read_b128 v[4:7], v19 offset:16560
	ds_read2_b64 v[28:31], v32 offset0:96 offset1:112
	s_waitcnt lgkmcnt(4)
	v_pk_mul_f32 v[14:15], v[56:57], v[60:61]
	s_nop 0
	v_sub_f32_e32 v14, v14, v15
	v_mul_f32_e32 v56, v56, v61
	s_waitcnt lgkmcnt(3)
	v_mul_f32_e32 v14, v64, v14
	v_fmac_f32_e32 v56, v57, v60
	v_fma_f32 v56, -v65, v56, v14
	v_add_f32_e32 v60, v27, v56
	v_pk_mul_f32 v[56:57], v[58:59], v[62:63]
	s_nop 0
	v_sub_f32_e32 v56, v56, v57
	v_mul_f32_e32 v57, v58, v63
	v_mul_f32_e32 v56, v66, v56
	v_fmac_f32_e32 v57, v59, v62
	v_fma_f32 v56, -v67, v57, v56
	v_add_f32_e32 v27, v60, v56
	ds_read_b128 v[56:59], v18 offset:8384
	ds_read_b128 v[60:63], v19 offset:16576
	ds_read2_b64 v[64:67], v32 offset0:128 offset1:144
	s_waitcnt lgkmcnt(4)
	v_pk_mul_f32 v[14:15], v[0:1], v[4:5]
	s_nop 0
	v_sub_f32_e32 v14, v14, v15
	v_mul_f32_e32 v0, v0, v5
	s_waitcnt lgkmcnt(3)
	v_mul_f32_e32 v14, v28, v14
	v_fmac_f32_e32 v0, v1, v4
	v_fma_f32 v0, -v29, v0, v14
	v_add_f32_e32 v4, v27, v0
	v_pk_mul_f32 v[0:1], v[2:3], v[6:7]
	s_nop 0
	v_sub_f32_e32 v0, v0, v1
	v_mul_f32_e32 v1, v2, v7
	v_mul_f32_e32 v0, v30, v0
	v_fmac_f32_e32 v1, v3, v6
	v_fma_f32 v0, -v31, v1, v0
	v_add_f32_e32 v27, v4, v0
	ds_read_b128 v[0:3], v18 offset:8400
	ds_read_b128 v[4:7], v19 offset:16592
	ds_read2_b64 v[28:31], v32 offset0:160 offset1:176
	s_waitcnt lgkmcnt(4)
	v_pk_mul_f32 v[14:15], v[56:57], v[60:61]
	s_nop 0
	v_sub_f32_e32 v14, v14, v15
	v_mul_f32_e32 v56, v56, v61
	s_waitcnt lgkmcnt(3)
	v_mul_f32_e32 v14, v64, v14
	v_fmac_f32_e32 v56, v57, v60
	v_fma_f32 v56, -v65, v56, v14
	v_add_f32_e32 v60, v27, v56
	v_pk_mul_f32 v[56:57], v[58:59], v[62:63]
	s_nop 0
	v_sub_f32_e32 v56, v56, v57
	v_mul_f32_e32 v57, v58, v63
	v_mul_f32_e32 v56, v66, v56
	v_fmac_f32_e32 v57, v59, v62
	v_fma_f32 v56, -v67, v57, v56
	v_add_f32_e32 v27, v60, v56
	ds_read_b128 v[56:59], v18 offset:8416
	ds_read_b128 v[60:63], v19 offset:16608
	ds_read2_b64 v[64:67], v32 offset0:192 offset1:208
	s_waitcnt lgkmcnt(4)
	v_pk_mul_f32 v[14:15], v[0:1], v[4:5]
	s_nop 0
	v_sub_f32_e32 v14, v14, v15
	v_mul_f32_e32 v0, v0, v5
	s_waitcnt lgkmcnt(3)
	v_mul_f32_e32 v14, v28, v14
	v_fmac_f32_e32 v0, v1, v4
	v_fma_f32 v0, -v29, v0, v14
	v_add_f32_e32 v4, v27, v0
	v_pk_mul_f32 v[0:1], v[2:3], v[6:7]
	s_nop 0
	v_sub_f32_e32 v0, v0, v1
	v_mul_f32_e32 v1, v2, v7
	v_mul_f32_e32 v0, v30, v0
	v_fmac_f32_e32 v1, v3, v6
	v_fma_f32 v0, -v31, v1, v0
	v_add_f32_e32 v27, v4, v0
	ds_read_b128 v[0:3], v18 offset:8432
	ds_read_b128 v[4:7], v19 offset:16624
	ds_read2_b64 v[28:31], v32 offset0:224 offset1:240
	s_waitcnt lgkmcnt(4)
	v_pk_mul_f32 v[14:15], v[56:57], v[60:61]
	s_nop 0
	v_sub_f32_e32 v14, v14, v15
	v_mul_f32_e32 v56, v56, v61
	s_waitcnt lgkmcnt(3)
	v_mul_f32_e32 v14, v64, v14
	v_fmac_f32_e32 v56, v57, v60
	v_fma_f32 v56, -v65, v56, v14
	v_add_f32_e32 v60, v27, v56
	v_pk_mul_f32 v[56:57], v[58:59], v[62:63]
	s_nop 0
	v_sub_f32_e32 v56, v56, v57
	v_mul_f32_e32 v57, v58, v63
	v_mul_f32_e32 v56, v66, v56
	v_fmac_f32_e32 v57, v59, v62
	v_fma_f32 v56, -v67, v57, v56
	v_add_f32_e32 v27, v60, v56
	v_add_u32_e32 v32, 0x1000, v9
	ds_read_b128 v[56:59], v18 offset:8448
	ds_read_b128 v[60:63], v19 offset:16640
	ds_read2_b64 v[64:67], v32 offset1:16
	s_waitcnt lgkmcnt(4)
	v_pk_mul_f32 v[14:15], v[0:1], v[4:5]
	s_nop 0
	v_sub_f32_e32 v14, v14, v15
	v_mul_f32_e32 v0, v0, v5
	s_waitcnt lgkmcnt(3)
	v_mul_f32_e32 v14, v28, v14
	v_fmac_f32_e32 v0, v1, v4
	v_fma_f32 v0, -v29, v0, v14
	v_add_f32_e32 v4, v27, v0
	v_pk_mul_f32 v[0:1], v[2:3], v[6:7]
	s_nop 0
	v_sub_f32_e32 v0, v0, v1
	v_mul_f32_e32 v1, v2, v7
	v_mul_f32_e32 v0, v30, v0
	v_fmac_f32_e32 v1, v3, v6
	v_fma_f32 v0, -v31, v1, v0
	v_add_f32_e32 v27, v4, v0
	ds_read_b128 v[0:3], v18 offset:8464
	ds_read_b128 v[4:7], v19 offset:16656
	ds_read2_b64 v[28:31], v32 offset0:32 offset1:48
	s_waitcnt lgkmcnt(4)
	v_pk_mul_f32 v[14:15], v[56:57], v[60:61]
	s_nop 0
	v_sub_f32_e32 v14, v14, v15
	v_mul_f32_e32 v56, v56, v61
	s_waitcnt lgkmcnt(3)
	v_mul_f32_e32 v14, v64, v14
	v_fmac_f32_e32 v56, v57, v60
	v_fma_f32 v56, -v65, v56, v14
	v_add_f32_e32 v60, v27, v56
	v_pk_mul_f32 v[56:57], v[58:59], v[62:63]
	s_nop 0
	v_sub_f32_e32 v56, v56, v57
	v_mul_f32_e32 v57, v58, v63
	v_mul_f32_e32 v56, v66, v56
	v_fmac_f32_e32 v57, v59, v62
	v_fma_f32 v56, -v67, v57, v56
	v_add_f32_e32 v27, v60, v56
	ds_read_b128 v[56:59], v18 offset:8480
	ds_read_b128 v[60:63], v19 offset:16672
	ds_read2_b64 v[64:67], v32 offset0:64 offset1:80
	s_waitcnt lgkmcnt(4)
	v_pk_mul_f32 v[14:15], v[0:1], v[4:5]
	s_nop 0
	v_sub_f32_e32 v14, v14, v15
	v_mul_f32_e32 v0, v0, v5
	s_waitcnt lgkmcnt(3)
; __device__ __forceinline__ f32x2 cmul(f32x2 a, f32x2 b) { return (f32x2){a.x * b.x - a.y * b.y, a.x * b.y + a.y * b.x}; }
; __device__ __forceinline__ void ssm_tables(const Args& a, LAS unsigned char* lds, int l, int g, const int tid) {
;     ...
;     for (int idx = tid; idx < 4096; idx += 512) { const int tau = idx >> 8, c = (idx >> 4) & 15, c2 = idx & 15; float s = 0.f;
;         for (int p = 0; p < 64; ++p) { const f32x2 w = cmul(sC[c * 64 + p], sP[tau * 64 + p]); const f32x2 b = sB[p * 16 + c2]; s += w.x * b.x - w.y * b.y; }
;         sK[idx] = s; }
	v_mul_f32_e32 v14, v28, v14
	v_fmac_f32_e32 v0, v1, v4
	v_fma_f32 v0, -v29, v0, v14
	v_add_f32_e32 v4, v27, v0
	v_pk_mul_f32 v[0:1], v[2:3], v[6:7]
	s_nop 0
	v_sub_f32_e32 v0, v0, v1
	v_mul_f32_e32 v1, v2, v7
	v_mul_f32_e32 v0, v30, v0
	v_fmac_f32_e32 v1, v3, v6
	v_fma_f32 v0, -v31, v1, v0
	v_add_f32_e32 v27, v4, v0
	ds_read_b128 v[0:3], v18 offset:8496
	ds_read_b128 v[4:7], v19 offset:16688
	ds_read2_b64 v[28:31], v32 offset0:96 offset1:112
	s_waitcnt lgkmcnt(4)
	v_pk_mul_f32 v[14:15], v[56:57], v[60:61]
	s_nop 0
	v_sub_f32_e32 v14, v14, v15
	v_mul_f32_e32 v56, v56, v61
	s_waitcnt lgkmcnt(3)
	v_mul_f32_e32 v14, v64, v14
	v_fmac_f32_e32 v56, v57, v60
	v_fma_f32 v56, -v65, v56, v14
	v_add_f32_e32 v60, v27, v56
	v_pk_mul_f32 v[56:57], v[58:59], v[62:63]
	s_nop 0
	v_sub_f32_e32 v56, v56, v57
	v_mul_f32_e32 v57, v58, v63
	v_mul_f32_e32 v56, v66, v56
	v_fmac_f32_e32 v57, v59, v62
	v_fma_f32 v56, -v67, v57, v56
	v_add_f32_e32 v27, v60, v56
	ds_read_b128 v[56:59], v18 offset:8512
	ds_read_b128 v[60:63], v19 offset:16704
	ds_read2_b64 v[64:67], v32 offset0:128 offset1:144
	s_waitcnt lgkmcnt(4)
	v_pk_mul_f32 v[14:15], v[0:1], v[4:5]
	s_nop 0
	v_sub_f32_e32 v14, v14, v15
	v_mul_f32_e32 v0, v0, v5
	s_waitcnt lgkmcnt(3)
	v_mul_f32_e32 v14, v28, v14
	v_fmac_f32_e32 v0, v1, v4
	v_fma_f32 v0, -v29, v0, v14
	v_add_f32_e32 v4, v27, v0
	v_pk_mul_f32 v[0:1], v[2:3], v[6:7]
	s_nop 0
	v_sub_f32_e32 v0, v0, v1
	v_mul_f32_e32 v1, v2, v7
	v_mul_f32_e32 v0, v30, v0
	v_fmac_f32_e32 v1, v3, v6
	v_fma_f32 v0, -v31, v1, v0
	v_add_f32_e32 v27, v4, v0
	ds_read_b128 v[0:3], v18 offset:8528
	ds_read_b128 v[4:7], v19 offset:16720
	ds_read2_b64 v[28:31], v32 offset0:160 offset1:176
	s_waitcnt lgkmcnt(4)
	v_pk_mul_f32 v[14:15], v[56:57], v[60:61]
	s_nop 0
	v_sub_f32_e32 v14, v14, v15
	v_mul_f32_e32 v56, v56, v61
	s_waitcnt lgkmcnt(3)
	v_mul_f32_e32 v14, v64, v14
	v_fmac_f32_e32 v56, v57, v60
	v_fma_f32 v56, -v65, v56, v14
	v_add_f32_e32 v60, v27, v56
	v_pk_mul_f32 v[56:57], v[58:59], v[62:63]
	s_nop 0
	v_sub_f32_e32 v56, v56, v57
	v_mul_f32_e32 v57, v58, v63
	v_mul_f32_e32 v56, v66, v56
	v_fmac_f32_e32 v57, v59, v62
	v_fma_f32 v56, -v67, v57, v56
	v_add_f32_e32 v27, v60, v56
	ds_read_b128 v[56:59], v18 offset:8544
	ds_read_b128 v[60:63], v19 offset:16736
	ds_read2_b64 v[64:67], v32 offset0:192 offset1:208
	s_waitcnt lgkmcnt(4)
	v_pk_mul_f32 v[14:15], v[0:1], v[4:5]
	s_nop 0
	v_sub_f32_e32 v14, v14, v15
	v_mul_f32_e32 v0, v0, v5
	s_waitcnt lgkmcnt(3)
	v_mul_f32_e32 v14, v28, v14
	v_fmac_f32_e32 v0, v1, v4
	v_fma_f32 v0, -v29, v0, v14
	v_add_f32_e32 v4, v27, v0
	v_pk_mul_f32 v[0:1], v[2:3], v[6:7]
	s_nop 0
	v_sub_f32_e32 v0, v0, v1
	v_mul_f32_e32 v1, v2, v7
	v_mul_f32_e32 v0, v30, v0
	v_fmac_f32_e32 v1, v3, v6
	v_fma_f32 v0, -v31, v1, v0
	v_add_f32_e32 v27, v4, v0
	ds_read_b128 v[0:3], v18 offset:8560
	ds_read_b128 v[4:7], v19 offset:16752
	ds_read2_b64 v[28:31], v32 offset0:224 offset1:240
	s_waitcnt lgkmcnt(4)
	v_pk_mul_f32 v[14:15], v[56:57], v[60:61]
	s_nop 0
	v_sub_f32_e32 v14, v14, v15
	v_mul_f32_e32 v56, v56, v61
	s_waitcnt lgkmcnt(3)
	v_mul_f32_e32 v14, v64, v14
	v_fmac_f32_e32 v56, v57, v60
	v_fma_f32 v56, -v65, v56, v14
	v_add_f32_e32 v60, v27, v56
	v_pk_mul_f32 v[56:57], v[58:59], v[62:63]
	s_nop 0
	v_sub_f32_e32 v56, v56, v57
	v_mul_f32_e32 v57, v58, v63
	v_mul_f32_e32 v56, v66, v56
	v_fmac_f32_e32 v57, v59, v62
	v_fma_f32 v56, -v67, v57, v56
	v_add_f32_e32 v27, v60, v56
	ds_read_b128 v[56:59], v18 offset:8576
	ds_read_b128 v[60:63], v19 offset:16768
	ds_read2_b64 v[64:67], v34 offset1:16
	s_waitcnt lgkmcnt(4)
	v_pk_mul_f32 v[14:15], v[0:1], v[4:5]
	s_nop 0
	v_sub_f32_e32 v14, v14, v15
	v_mul_f32_e32 v0, v0, v5
	s_waitcnt lgkmcnt(3)
	v_mul_f32_e32 v14, v28, v14
	v_fmac_f32_e32 v0, v1, v4
	v_fma_f32 v0, -v29, v0, v14
	v_add_f32_e32 v4, v27, v0
	v_pk_mul_f32 v[0:1], v[2:3], v[6:7]
	s_nop 0
	v_sub_f32_e32 v0, v0, v1
	v_mul_f32_e32 v1, v2, v7
	v_mul_f32_e32 v0, v30, v0
	v_fmac_f32_e32 v1, v3, v6
	v_fma_f32 v0, -v31, v1, v0
	v_add_f32_e32 v27, v4, v0
	ds_read_b128 v[0:3], v18 offset:8592
	ds_read_b128 v[4:7], v19 offset:16784
	ds_read2_b64 v[28:31], v34 offset0:32 offset1:48
	s_waitcnt lgkmcnt(4)
	v_pk_mul_f32 v[14:15], v[56:57], v[60:61]
	s_nop 0
	v_sub_f32_e32 v14, v14, v15
	v_mul_f32_e32 v56, v56, v61
	s_waitcnt lgkmcnt(3)
	v_mul_f32_e32 v14, v64, v14
	v_fmac_f32_e32 v56, v57, v60
	v_fma_f32 v56, -v65, v56, v14
	v_add_f32_e32 v60, v27, v56
	v_pk_mul_f32 v[56:57], v[58:59], v[62:63]
	s_nop 0
	v_sub_f32_e32 v56, v56, v57
	v_mul_f32_e32 v57, v58, v63
	v_mul_f32_e32 v56, v66, v56
	v_fmac_f32_e32 v57, v59, v62
	v_fma_f32 v56, -v67, v57, v56
	v_add_f32_e32 v27, v60, v56
	ds_read_b128 v[56:59], v18 offset:8608
	ds_read_b128 v[60:63], v19 offset:16800
	ds_read2_b64 v[64:67], v34 offset0:64 offset1:80
	s_waitcnt lgkmcnt(4)
	v_pk_mul_f32 v[14:15], v[0:1], v[4:5]
	s_nop 0
	v_sub_f32_e32 v14, v14, v15
	v_mul_f32_e32 v0, v0, v5
	s_waitcnt lgkmcnt(3)
; __device__ __forceinline__ f32x2 cmul(f32x2 a, f32x2 b) { return (f32x2){a.x * b.x - a.y * b.y, a.x * b.y + a.y * b.x}; }
; __device__ __forceinline__ void ssm_tables(const Args& a, LAS unsigned char* lds, int l, int g, const int tid) {
;     ...
;     for (int idx = tid; idx < 4096; idx += 512) { const int tau = idx >> 8, c = (idx >> 4) & 15, c2 = idx & 15; float s = 0.f;
;         for (int p = 0; p < 64; ++p) { const f32x2 w = cmul(sC[c * 64 + p], sP[tau * 64 + p]); const f32x2 b = sB[p * 16 + c2]; s += w.x * b.x - w.y * b.y; }
;         sK[idx] = s; }
	v_mul_f32_e32 v14, v28, v14
	v_fmac_f32_e32 v0, v1, v4
	v_fma_f32 v0, -v29, v0, v14
	v_add_f32_e32 v4, v27, v0
	v_pk_mul_f32 v[0:1], v[2:3], v[6:7]
	s_nop 0
	v_sub_f32_e32 v0, v0, v1
	v_mul_f32_e32 v1, v2, v7
	v_mul_f32_e32 v0, v30, v0
	v_fmac_f32_e32 v1, v3, v6
	v_fma_f32 v0, -v31, v1, v0
	v_add_f32_e32 v27, v4, v0
	ds_read_b128 v[0:3], v18 offset:8624
	ds_read_b128 v[4:7], v19 offset:16816
	ds_read2_b64 v[28:31], v34 offset0:96 offset1:112
	s_waitcnt lgkmcnt(5)
	v_mov_b32_e32 v15, v58
	s_waitcnt lgkmcnt(4)
	v_mov_b32_e32 v32, v60
	v_mov_b32_e32 v33, v62
	v_mov_b32_e32 v58, v57
	v_mov_b32_e32 v62, v61
	v_mov_b32_e32 v14, v56
	v_pk_mul_f32 v[56:57], v[58:59], v[62:63]
	v_pk_mul_f32 v[58:59], v[58:59], v[32:33]
	s_waitcnt lgkmcnt(3)
	v_mov_b32_e32 v61, v66
	v_pk_fma_f32 v[58:59], v[14:15], v[62:63], v[58:59]
	v_mov_b32_e32 v66, v65
	v_pk_fma_f32 v[56:57], v[14:15], v[32:33], v[56:57] neg_lo:[0,0,1] neg_hi:[0,0,1]
	v_mov_b32_e32 v60, v64
	v_pk_mul_f32 v[58:59], v[66:67], v[58:59]
	s_nop 0
	v_pk_fma_f32 v[56:57], v[60:61], v[56:57], v[58:59] neg_lo:[0,0,1] neg_hi:[0,0,1]
	s_nop 0
	v_add_f32_e32 v56, v27, v56
	v_add_f32_e32 v27, v56, v57
	ds_read_b128 v[56:59], v18 offset:8640
	ds_read_b128 v[60:63], v19 offset:16832
	ds_read2_b64 v[64:67], v34 offset0:128 offset1:144
	s_waitcnt lgkmcnt(5)
	v_mov_b32_e32 v15, v2
	s_waitcnt lgkmcnt(4)
	v_mov_b32_e32 v32, v4
	v_mov_b32_e32 v33, v6
	v_mov_b32_e32 v2, v1
	v_mov_b32_e32 v6, v5
	v_mov_b32_e32 v14, v0
	v_pk_mul_f32 v[0:1], v[2:3], v[6:7]
	v_pk_mul_f32 v[2:3], v[2:3], v[32:33]
	s_waitcnt lgkmcnt(3)
	v_mov_b32_e32 v5, v30
	v_pk_fma_f32 v[2:3], v[14:15], v[6:7], v[2:3]
	v_mov_b32_e32 v30, v29
	v_pk_fma_f32 v[0:1], v[14:15], v[32:33], v[0:1] neg_lo:[0,0,1] neg_hi:[0,0,1]
	v_mov_b32_e32 v4, v28
	v_pk_mul_f32 v[2:3], v[30:31], v[2:3]
	s_nop 0
	v_pk_fma_f32 v[0:1], v[4:5], v[0:1], v[2:3] neg_lo:[0,0,1] neg_hi:[0,0,1]
	s_nop 0
	v_add_f32_e32 v0, v27, v0
	v_add_f32_e32 v27, v0, v1
	ds_read_b128 v[0:3], v18 offset:8656
	ds_read_b128 v[4:7], v19 offset:16848
	ds_read2_b64 v[28:31], v34 offset0:160 offset1:176
	s_waitcnt lgkmcnt(5)
	v_mov_b32_e32 v15, v58
	s_waitcnt lgkmcnt(4)
	v_mov_b32_e32 v32, v60
	v_mov_b32_e32 v33, v62
	v_mov_b32_e32 v58, v57
	v_mov_b32_e32 v62, v61
	v_mov_b32_e32 v14, v56
	v_pk_mul_f32 v[56:57], v[58:59], v[62:63]
	v_pk_mul_f32 v[58:59], v[58:59], v[32:33]
	s_waitcnt lgkmcnt(3)
	v_mov_b32_e32 v61, v66
	v_pk_fma_f32 v[58:59], v[14:15], v[62:63], v[58:59]
	v_mov_b32_e32 v66, v65
	v_pk_fma_f32 v[56:57], v[14:15], v[32:33], v[56:57] neg_lo:[0,0,1] neg_hi:[0,0,1]
	v_mov_b32_e32 v60, v64
	v_pk_mul_f32 v[58:59], v[66:67], v[58:59]
	s_nop 0
	v_pk_fma_f32 v[56:57], v[60:61], v[56:57], v[58:59] neg_lo:[0,0,1] neg_hi:[0,0,1]
	s_nop 0
	v_add_f32_e32 v56, v27, v56
	v_add_f32_e32 v27, v56, v57
	ds_read_b128 v[56:59], v18 offset:8672
	ds_read_b128 v[60:63], v19 offset:16864
	ds_read2_b64 v[64:67], v34 offset0:192 offset1:208
	s_waitcnt lgkmcnt(5)
	v_mov_b32_e32 v15, v2
	s_waitcnt lgkmcnt(4)
	v_mov_b32_e32 v32, v4
	v_mov_b32_e32 v33, v6
	v_mov_b32_e32 v2, v1
	v_mov_b32_e32 v6, v5
	v_mov_b32_e32 v14, v0
	v_pk_mul_f32 v[0:1], v[2:3], v[6:7]
	v_pk_mul_f32 v[2:3], v[2:3], v[32:33]
	s_waitcnt lgkmcnt(3)
	v_mov_b32_e32 v5, v30
	v_pk_fma_f32 v[2:3], v[14:15], v[6:7], v[2:3]
	v_mov_b32_e32 v30, v29
	v_pk_fma_f32 v[0:1], v[14:15], v[32:33], v[0:1] neg_lo:[0,0,1] neg_hi:[0,0,1]
	v_mov_b32_e32 v4, v28
	v_pk_mul_f32 v[2:3], v[30:31], v[2:3]
	s_nop 0
	v_pk_fma_f32 v[0:1], v[4:5], v[0:1], v[2:3] neg_lo:[0,0,1] neg_hi:[0,0,1]
	s_nop 0
	v_add_f32_e32 v0, v27, v0
	v_add_f32_e32 v27, v0, v1
	ds_read_b128 v[0:3], v18 offset:8688
	ds_read_b128 v[4:7], v19 offset:16880
	ds_read2_b64 v[28:31], v34 offset0:224 offset1:240
	s_waitcnt lgkmcnt(5)
	v_mov_b32_e32 v15, v58
	s_waitcnt lgkmcnt(4)
	v_mov_b32_e32 v32, v60
	v_mov_b32_e32 v33, v62
	v_mov_b32_e32 v58, v57
	v_mov_b32_e32 v62, v61
	v_mov_b32_e32 v14, v56
	v_pk_mul_f32 v[56:57], v[58:59], v[62:63]
	v_pk_mul_f32 v[58:59], v[58:59], v[32:33]
	s_waitcnt lgkmcnt(3)
	v_mov_b32_e32 v61, v66
	v_pk_fma_f32 v[58:59], v[14:15], v[62:63], v[58:59]
	v_mov_b32_e32 v66, v65
	v_pk_fma_f32 v[56:57], v[14:15], v[32:33], v[56:57] neg_lo:[0,0,1] neg_hi:[0,0,1]
	v_mov_b32_e32 v60, v64
	v_pk_mul_f32 v[58:59], v[66:67], v[58:59]
	s_nop 0
	v_pk_fma_f32 v[56:57], v[60:61], v[56:57], v[58:59] neg_lo:[0,0,1] neg_hi:[0,0,1]
	s_nop 0
	v_add_f32_e32 v56, v27, v56
	v_add_f32_e32 v27, v56, v57
	s_waitcnt lgkmcnt(2)
	v_mov_b32_e32 v15, v2
	s_waitcnt lgkmcnt(1)
	v_mov_b32_e32 v18, v4
	v_mov_b32_e32 v19, v6
	v_mov_b32_e32 v2, v1
	v_mov_b32_e32 v6, v5
	v_mov_b32_e32 v14, v0
	v_pk_mul_f32 v[0:1], v[2:3], v[6:7]
	v_pk_mul_f32 v[2:3], v[2:3], v[18:19]
	s_waitcnt lgkmcnt(0)
	v_mov_b32_e32 v5, v30
	v_pk_fma_f32 v[2:3], v[14:15], v[6:7], v[2:3]
	v_mov_b32_e32 v30, v29
	v_pk_fma_f32 v[0:1], v[14:15], v[18:19], v[0:1] neg_lo:[0,0,1] neg_hi:[0,0,1]
	v_mov_b32_e32 v4, v28
	v_pk_mul_f32 v[2:3], v[30:31], v[2:3]
	s_nop 0
	v_pk_fma_f32 v[0:1], v[4:5], v[0:1], v[2:3] neg_lo:[0,0,1] neg_hi:[0,0,1]
	s_nop 0
	v_add_f32_e32 v0, v27, v0
	v_add_f32_e32 v0, v0, v1
	v_add_u32_e32 v1, 0, v16
	ds_write_b32 v1, v0 offset:25600
	v_add_u32_e32 v0, 0x200, v17
	v_add_u32_e32 v16, 0x800, v16
	v_mov_b32_e32 v17, v0
	s_andn2_b64 exec, exec, s[14:15]
	s_cbranch_execnz .LBB0_745

; __device__ __forceinline__ unsigned pk2(float lo, float hi) { return pg8::cvt_pk_bf16(lo, hi); }
; __device__ __forceinline__ f32x2 cmul(f32x2 a, f32x2 b) { return (f32x2){a.x * b.x - a.y * b.y, a.x * b.y + a.y * b.x}; }
; __device__ __forceinline__ void ssm_tables(const Args& a, LAS unsigned char* lds, int l, int g, const int tid) {
;     ...
;     for (int v = tid; v < 256 * 48; v += 512) { const int row = v / 48, k0 = (v % 48) * 8, t = row >> 4, c = row & 15; float o[8];
;         if (k0 < 256) { const int s = k0 >> 4, c0 = k0 & 15;
; #pragma unroll
;             for (int e = 0; e < 8; ++e) o[e] = (s <= t) ? sK[((t - s) * 16 + c) * 16 + c0 + e] : 0.f;
;         } else { const int kk = k0 - 256;
; #pragma unroll
;             for (int e = 0; e < 8; ++e) { const int p = (kk + e) >> 1; const f32x2 w = cmul(sC[c * 64 + p], sP[(t + 1) * 64 + p]); o[e] = (e & 1) ? -w.y : w.x; }
;         }
;         u32x4 w; w.x = pk2(o[0], o[1]); w.y = pk2(o[2], o[3]); w.z = pk2(o[4], o[5]); w.w = pk2(o[6], o[7]);
.LBB0_752:
	s_mov_b32 s22, 0x2aaaaaab
	v_mul_hi_i32 v1, v2, s22
	v_lshrrev_b32_e32 v3, 31, v1
	v_ashrrev_i32_e32 v1, 3, v1
	v_add_u32_e32 v1, v1, v3
	s_movk_i32 s22, 0xffd0
	v_mad_u64_u32 v[18:19], s[22:23], v1, s22, v[2:3]
	s_movk_i32 s22, 0xfe80
	s_nop 0
	v_mad_u64_u32 v[4:5], s[22:23], v1, s22, v[0:1]
	v_ashrrev_i32_e32 v19, 4, v1
	v_and_b32_e32 v27, 15, v1
	v_cmp_lt_i32_e32 vcc, 31, v18
	s_and_saveexec_b64 s[22:23], vcc
	s_xor_b64 s[22:23], exec, s[22:23]
	s_cbranch_execz .LBB0_754
	v_lshlrev_b32_e32 v32, 2, v4
	v_lshl_add_u32 v27, v27, 9, v32
	v_lshl_add_u32 v31, v19, 9, v32
	ds_read_b64 v[56:57], v27 offset:7168
	ds_read_b64 v[64:65], v31 offset:15872
	ds_read_b64 v[58:59], v27 offset:7176
	ds_read_b64 v[66:67], v31 offset:15880
	ds_read_b64 v[60:61], v27 offset:7184
	ds_read_b64 v[68:69], v31 offset:15888
	ds_read_b64 v[62:63], v27 offset:7192
	ds_read_b64 v[70:71], v31 offset:15896
	s_waitcnt lgkmcnt(0)
	v_mul_f32_e32 v18, v57, v65
	v_mul_f32_e32 v19, v56, v65
	v_fma_f32 v15, v56, v64, -v18
	v_fma_f32 v3, -v57, v64, -v19
	v_mul_f32_e32 v18, v59, v67
	v_mul_f32_e32 v19, v58, v67
	v_fma_f32 v6, v58, v66, -v18
	v_fma_f32 v5, -v59, v66, -v19
	v_mul_f32_e32 v18, v61, v69
	v_mul_f32_e32 v19, v60, v69
	v_fma_f32 v14, v60, v68, -v18
	v_fma_f32 v7, -v61, v68, -v19
	v_mul_f32_e32 v18, v63, v71
	v_mul_f32_e32 v19, v62, v71
	v_fma_f32 v16, v62, v70, -v18
	v_fma_f32 v17, -v63, v70, -v19
